# final RMSNorm loop (P17): next row prefetched into a second register set before the store ladder, counted vmcnt(8) at the loop top
# speedup vs baseline: 1.0012x; 1.0012x over previous
; __device__ __forceinline__ void rms_row_f32(float* xrow, const float* g, int lane) {
;     f32x4 v[8]; float s = 0.f;
; #pragma unroll
;     for (int j = 0; j < 8; ++j) { v[j] = __builtin_nontemporal_load((const f32x4*)xrow + lane + 64 * j); s += (v[j][0] * v[j][0] + v[j][1] * v[j][1]) + (v[j][2] * v[j][2] + v[j][3] * v[j][3]); }
;     const float rstd = rsqrtf(wave_sum(s) * (1.f / D) + EPS);
; #pragma unroll
;     for (int j = 0; j < 8; ++j) { const f32x4 gg = ((const f32x4*)g)[lane + 64 * j]; __builtin_nontemporal_store(v[j] * rstd * gg, (f32x4*)xrow + lane + 64 * j); }
; }
; __global__ void __launch_bounds__(NTHREADS, 2) fwd_kernel(Args args) {
;     ...
;     if (IN(17)) { for (int m = gw; m < T; m += NGW) rms_row_f32(out + (size_t)m * D, final_norm, lane); }
.LBB0_1509:
	s_cmp_lt_i32 s90, 18
	s_cselect_b64 s[0:1], -1, 0
	s_and_b64 s[0:1], s[0:1], s[2:3]
	s_cmp_lt_i32 s48, 0x8000
	s_cselect_b64 s[2:3], -1, 0
	s_and_b64 s[0:1], s[0:1], s[2:3]
	s_andn2_b64 vcc, exec, s[0:1]
	s_cbranch_vccnz .LBB0_1512
	v_mbcnt_lo_u32_b32 v0, -1, 0
	v_mbcnt_hi_u32_b32 v0, -1, v0
	v_and_b32_e32 v1, 64, v0
	v_add_u32_e32 v1, 64, v1
	v_xor_b32_e32 v2, 1, v0
	v_cmp_lt_i32_e32 vcc, v2, v1
	v_lshlrev_b32_e32 v10, 4, v176
	v_mov_b32_e32 v11, 0
	v_cndmask_b32_e32 v2, v0, v2, vcc
	v_lshlrev_b32_e32 v12, 2, v2
	v_xor_b32_e32 v2, 2, v0
	v_cmp_lt_i32_e32 vcc, v2, v1
	s_ashr_i32 s49, s48, 31
	s_mov_b64 s[0:1], 0x1000
	v_cndmask_b32_e32 v2, v0, v2, vcc
	v_lshlrev_b32_e32 v13, 2, v2
	v_xor_b32_e32 v2, 4, v0
	v_cmp_lt_i32_e32 vcc, v2, v1
	s_lshl_b64 s[2:3], s[48:49], 13
	s_add_u32 s2, s86, s2
	v_cndmask_b32_e32 v2, v0, v2, vcc
	v_lshlrev_b32_e32 v14, 2, v2
	v_xor_b32_e32 v2, 8, v0
	v_cmp_lt_i32_e32 vcc, v2, v1
	s_addc_u32 s3, s87, s3
	s_ashr_i32 s37, s36, 31
	v_cndmask_b32_e32 v2, v0, v2, vcc
	v_lshlrev_b32_e32 v15, 2, v2
	v_xor_b32_e32 v2, 16, v0
	v_cmp_lt_i32_e32 vcc, v2, v1
	v_mov_b32_e32 v18, 0x358637bd
	s_nop 0
	v_cndmask_b32_e32 v2, v0, v2, vcc
	v_lshlrev_b32_e32 v16, 2, v2
	v_xor_b32_e32 v2, 32, v0
	v_cmp_lt_i32_e32 vcc, v2, v1
	s_nop 1
	v_cndmask_b32_e32 v0, v0, v2, vcc
	v_lshlrev_b32_e32 v17, 2, v0
	v_lshl_add_u64 v[0:1], s[84:85], 0, v[10:11]
	v_lshl_add_u64 v[2:3], v[0:1], 0, s[0:1]
	s_mov_b64 s[0:1], 0x1400
	v_lshl_add_u64 v[4:5], v[0:1], 0, s[0:1]
	s_mov_b64 s[0:1], 0x1800
	v_lshl_add_u64 v[6:7], v[0:1], 0, s[0:1]
	s_mov_b64 s[0:1], 0x1c00
	v_lshl_add_u64 v[10:11], s[2:3], 0, v[10:11]
	v_lshl_add_u64 v[8:9], v[0:1], 0, s[0:1]
	v_lshl_add_u64 v[10:11], v[10:11], 0, s[0:1]
	s_lshl_b64 s[0:1], s[36:37], 13
	s_mov_b32 s2, 0x800000
	global_load_dwordx4 v[88:91], v[0:1], off
	global_load_dwordx4 v[92:95], v[0:1], off offset:1024
	global_load_dwordx4 v[96:99], v[0:1], off offset:2048
	global_load_dwordx4 v[100:103], v[0:1], off offset:3072
	global_load_dwordx4 v[104:107], v[2:3], off
	global_load_dwordx4 v[108:111], v[4:5], off
	global_load_dwordx4 v[112:115], v[6:7], off
	global_load_dwordx4 v[116:119], v[8:9], off
	v_add_co_u32_e32 v56, vcc, 0xfffff000, v10
	s_nop 1
	v_addc_co_u32_e32 v57, vcc, -1, v11, vcc
	global_load_dwordx4 v[120:123], v[10:11], off offset:-3072 nt
	global_load_dwordx4 v[124:127], v[10:11], off offset:-2048 nt
	global_load_dwordx4 v[128:131], v[10:11], off nt
	global_load_dwordx4 v[132:135], v[10:11], off offset:-1024 nt
	global_load_dwordx4 v[136:139], v[56:57], off offset:-3072 nt
	global_load_dwordx4 v[140:143], v[56:57], off offset:-2048 nt
	global_load_dwordx4 v[144:147], v[56:57], off offset:-1024 nt
	global_load_dwordx4 v[148:151], v[10:11], off offset:-4096 nt
	s_waitcnt vmcnt(0)
.LBB0_1511:
	s_waitcnt vmcnt(8)
	v_mov_b32_e32 v20, v120
	v_mov_b32_e32 v21, v121
	v_mov_b32_e32 v22, v122
	v_mov_b32_e32 v23, v123
	v_mov_b32_e32 v24, v124
	v_mov_b32_e32 v25, v125
	v_mov_b32_e32 v26, v126
	v_mov_b32_e32 v27, v127
	v_mov_b32_e32 v28, v128
	v_mov_b32_e32 v29, v129
	v_mov_b32_e32 v30, v130
	v_mov_b32_e32 v31, v131
	v_mov_b32_e32 v32, v132
	v_mov_b32_e32 v33, v133
	v_mov_b32_e32 v34, v134
	v_mov_b32_e32 v35, v135
	v_mov_b32_e32 v36, v136
	v_mov_b32_e32 v37, v137
	v_mov_b32_e32 v38, v138
	v_mov_b32_e32 v39, v139
	v_mov_b32_e32 v40, v140
	v_mov_b32_e32 v41, v141
	v_mov_b32_e32 v42, v142
	v_mov_b32_e32 v43, v143
	v_mov_b32_e32 v44, v144
	v_mov_b32_e32 v45, v145
	v_mov_b32_e32 v46, v146
	v_mov_b32_e32 v47, v147
	v_mov_b32_e32 v48, v148
	v_mov_b32_e32 v49, v149
	v_mov_b32_e32 v50, v150
	v_mov_b32_e32 v51, v151
	v_add_co_u32_e32 v56, vcc, 0xfffff000, v10
	s_add_i32 s48, s48, s36
	s_nop 0
	v_addc_co_u32_e32 v57, vcc, -1, v11, vcc
	s_cmp_lt_i32 s48, 0x8000
	s_cbranch_scc0 .Lp17_nopf
	v_lshl_add_u64 v[152:153], v[10:11], 0, s[0:1]
	v_add_co_u32_e32 v154, vcc, 0xfffff000, v152
	s_nop 1
	v_addc_co_u32_e32 v155, vcc, -1, v153, vcc
	global_load_dwordx4 v[120:123], v[152:153], off offset:-3072 nt
	global_load_dwordx4 v[124:127], v[152:153], off offset:-2048 nt
	global_load_dwordx4 v[128:131], v[152:153], off nt
	global_load_dwordx4 v[132:135], v[152:153], off offset:-1024 nt
	global_load_dwordx4 v[136:139], v[154:155], off offset:-3072 nt
	global_load_dwordx4 v[140:143], v[154:155], off offset:-2048 nt
	global_load_dwordx4 v[144:147], v[154:155], off offset:-1024 nt
	global_load_dwordx4 v[148:151], v[152:153], off offset:-4096 nt
; __device__ __forceinline__ void rms_row_f32(float* xrow, const float* g, int lane) {
;     ...
;     for (int j = 0; j < 8; ++j) { v[j] = __builtin_nontemporal_load((const f32x4*)xrow + lane + 64 * j); s += (v[j][0] * v[j][0] + v[j][1] * v[j][1]) + (v[j][2] * v[j][2] + v[j][3] * v[j][3]); }
;     const float rstd = rsqrtf(wave_sum(s) * (1.f / D) + EPS);
; #pragma unroll
;     for (int j = 0; j < 8; ++j) { const f32x4 gg = ((const f32x4*)g)[lane + 64 * j]; __builtin_nontemporal_store(v[j] * rstd * gg, (f32x4*)xrow + lane + 64 * j); }
; }
.Lp17_nopf:
	v_mul_f32_e32 v81, v21, v21
	v_pk_mul_f32 v[58:59], v[26:27], v[26:27]
	v_pk_mul_f32 v[60:61], v[24:25], v[24:25]
	v_mul_f32_e32 v62, v33, v33
	v_mul_f32_e32 v64, v35, v35
	v_mul_f32_e32 v79, v30, v30
	v_mul_f32_e32 v86, v31, v31
	v_pk_mov_b32 v[66:67], v[60:61], v[58:59] op_sel:[1,0]
	v_mov_b32_e32 v61, v59
	v_pk_fma_f32 v[58:59], v[32:33], v[32:33], v[62:63] op_sel_hi:[1,1,0]
	v_pk_fma_f32 v[62:63], v[34:35], v[34:35], v[64:65] op_sel_hi:[1,1,0]
	v_mov_b32_e32 v68, v37
	v_mov_b32_e32 v69, v41
	v_mov_b32_e32 v72, v39
	v_mov_b32_e32 v73, v43
	v_mov_b32_e32 v64, v36
	v_mov_b32_e32 v65, v40
	v_mov_b32_e32 v70, v38
	v_mov_b32_e32 v71, v42
	v_pk_mul_f32 v[74:75], v[46:47], v[46:47]
	v_pk_mul_f32 v[76:77], v[44:45], v[44:45]
	v_pk_add_f32 v[60:61], v[66:67], v[60:61]
	v_mov_b32_e32 v59, v79
	v_mov_b32_e32 v63, v86
	v_pk_mul_f32 v[66:67], v[68:69], v[68:69]
	v_pk_mul_f32 v[68:69], v[72:73], v[72:73]
	v_pk_mov_b32 v[72:73], v[76:77], v[74:75] op_sel:[1,0]
	v_mov_b32_e32 v77, v75
	v_pk_add_f32 v[58:59], v[58:59], v[62:63]
	v_pk_fma_f32 v[62:63], v[64:65], v[64:65], v[66:67]
	v_pk_fma_f32 v[64:65], v[70:71], v[70:71], v[68:69]
	v_mul_f32_e32 v78, v49, v49
	v_mul_f32_e32 v80, v51, v51
	v_pk_add_f32 v[66:67], v[72:73], v[76:77]
	v_pk_add_f32 v[62:63], v[62:63], v[64:65]
	v_mul_f32_e32 v19, v20, v20
	v_mul_f32_e32 v82, v22, v22
	v_mul_f32_e32 v83, v23, v23
	v_pk_fma_f32 v[74:75], v[48:49], v[48:49], v[78:79] op_sel_hi:[1,1,0]
	v_pk_fma_f32 v[78:79], v[50:51], v[50:51], v[80:81] op_sel_hi:[1,1,0]
	v_pk_add_f32 v[64:65], v[66:67], v[66:67] op_sel:[0,1] op_sel_hi:[1,0]
	v_pk_add_f32 v[62:63], v[62:63], v[62:63] op_sel:[0,1] op_sel_hi:[1,0]
	v_mov_b32_e32 v75, v82
	v_mov_b32_e32 v79, v83
	v_mov_b32_e32 v65, v81
	v_mov_b32_e32 v63, v19
	v_pk_add_f32 v[66:67], v[74:75], v[78:79]
	v_pk_add_f32 v[62:63], v[62:63], v[64:65]
	v_mul_f32_e32 v84, v28, v28
	v_pk_add_f32 v[62:63], v[62:63], v[66:67]
	v_mul_f32_e32 v85, v29, v29
	v_pk_add_f32 v[60:61], v[60:61], v[60:61] op_sel:[0,1] op_sel_hi:[1,0]
	v_pk_add_f32 v[62:63], v[62:63], v[62:63] op_sel:[0,1] op_sel_hi:[1,0]
	v_mov_b32_e32 v61, v85
	v_mov_b32_e32 v63, v84
	v_pk_add_f32 v[60:61], v[62:63], v[60:61]
	s_nop 0
	v_pk_add_f32 v[58:59], v[60:61], v[58:59]
	s_nop 0
	v_add_f32_e32 v19, v58, v59
	ds_bpermute_b32 v58, v12, v19
	s_waitcnt lgkmcnt(0)
	v_add_f32_e32 v19, v19, v58
	ds_bpermute_b32 v58, v13, v19
	s_waitcnt lgkmcnt(0)
	v_add_f32_e32 v19, v19, v58
	ds_bpermute_b32 v58, v14, v19
	s_waitcnt lgkmcnt(0)
	v_add_f32_e32 v19, v19, v58
	ds_bpermute_b32 v58, v15, v19
	s_waitcnt lgkmcnt(0)
	v_add_f32_e32 v19, v19, v58
	ds_bpermute_b32 v58, v16, v19
	s_waitcnt lgkmcnt(0)
	v_add_f32_e32 v19, v19, v58
	ds_bpermute_b32 v58, v17, v19
	s_waitcnt lgkmcnt(0)
	v_add_f32_e32 v19, v19, v58
	v_fmamk_f32 v19, v19, 0x3a000000, v18
	v_mul_f32_e32 v58, 0x4b800000, v19
	v_cmp_gt_f32_e32 vcc, s2, v19
	s_nop 1
	v_cndmask_b32_e32 v19, v19, v58, vcc
	v_rsq_f32_e32 v19, v19
	s_nop 0
	v_mul_f32_e32 v58, 0x45800000, v19
	v_cndmask_b32_e32 v58, v19, v58, vcc
	v_pk_mul_f32 v[36:37], v[36:37], v[58:59] op_sel_hi:[1,0]
	v_pk_mul_f32 v[38:39], v[38:39], v[58:59] op_sel_hi:[1,0]
	v_pk_mul_f32 v[36:37], v[88:89], v[36:37]
	v_pk_mul_f32 v[38:39], v[90:91], v[38:39]
	global_store_dwordx4 v[56:57], v[36:39], off offset:-3072 nt
	v_pk_mul_f32 v[42:43], v[42:43], v[58:59] op_sel_hi:[1,0]
	v_pk_mul_f32 v[40:41], v[40:41], v[58:59] op_sel_hi:[1,0]
	v_pk_mul_f32 v[22:23], v[22:23], v[58:59] op_sel_hi:[1,0]
	v_pk_mul_f32 v[20:21], v[20:21], v[58:59] op_sel_hi:[1,0]
	v_pk_mul_f32 v[26:27], v[26:27], v[58:59] op_sel_hi:[1,0]
	v_pk_mul_f32 v[24:25], v[24:25], v[58:59] op_sel_hi:[1,0]
	v_pk_mul_f32 v[36:37], v[92:93], v[40:41]
	v_pk_mul_f32 v[38:39], v[94:95], v[42:43]
	global_store_dwordx4 v[56:57], v[36:39], off offset:-2048 nt
	v_pk_mul_f32 v[40:41], v[46:47], v[58:59] op_sel_hi:[1,0]
	v_pk_mul_f32 v[42:43], v[44:45], v[58:59] op_sel_hi:[1,0]
	v_pk_mul_f32 v[38:39], v[98:99], v[40:41]
	v_pk_mul_f32 v[36:37], v[96:97], v[42:43]
	global_store_dwordx4 v[56:57], v[36:39], off offset:-1024 nt
	v_pk_mul_f32 v[40:41], v[50:51], v[58:59] op_sel_hi:[1,0]
	v_pk_mul_f32 v[42:43], v[48:49], v[58:59] op_sel_hi:[1,0]
	v_pk_mul_f32 v[38:39], v[102:103], v[40:41]
	v_pk_mul_f32 v[36:37], v[100:101], v[42:43]
	global_store_dwordx4 v[10:11], v[36:39], off offset:-4096 nt
	v_pk_mul_f32 v[20:21], v[104:105], v[20:21]
	v_pk_mul_f32 v[22:23], v[106:107], v[22:23]
	global_store_dwordx4 v[10:11], v[20:23], off offset:-3072 nt
	s_nop 1
	v_pk_mul_f32 v[20:21], v[108:109], v[24:25]
	v_pk_mul_f32 v[22:23], v[110:111], v[26:27]
	global_store_dwordx4 v[10:11], v[20:23], off offset:-2048 nt
	v_pk_mul_f32 v[24:25], v[34:35], v[58:59] op_sel_hi:[1,0]
	v_pk_mul_f32 v[26:27], v[32:33], v[58:59] op_sel_hi:[1,0]
	v_pk_mul_f32 v[22:23], v[24:25], v[114:115]
	v_pk_mul_f32 v[20:21], v[26:27], v[112:113]
	global_store_dwordx4 v[10:11], v[20:23], off offset:-1024 nt
	v_pk_mul_f32 v[24:25], v[30:31], v[58:59] op_sel_hi:[1,0]
	v_pk_mul_f32 v[26:27], v[28:29], v[58:59] op_sel_hi:[1,0]
	v_pk_mul_f32 v[22:23], v[24:25], v[118:119]
	v_pk_mul_f32 v[20:21], v[26:27], v[116:117]
	global_store_dwordx4 v[10:11], v[20:23], off nt
	v_lshl_add_u64 v[10:11], v[10:11], 0, s[0:1]
	s_cbranch_scc1 .LBB0_1511
